# FFN gate/up: next-tile rstd-table loads issued before the epilogue and waited with a counted vmcnt(8) after it (no full store drain at tile transitions)
# speedup vs baseline: 1.0080x; 1.0080x over previous
; #define PG8_LAS __attribute__((address_space(3)))
; __host__ __device__ __forceinline__ size_t tiled_off(int row, int col, int K) { return ((size_t)(row >> 7) * (K >> 6) + (col >> 6)) * 8192 + (lds_byte(row & 127, col & 63) >> 1); }
; __device__ __forceinline__ unsigned cvt_pk_bf16(float lo, float hi) { unsigned r; asm volatile("v_cvt_pk_bf16_f32 %0, %1, %2" : "=v"(r) : "v"(lo), "v"(hi)); return r; }
; __device__ __forceinline__ float fast_sigmoid(float x) { return __builtin_amdgcn_rcpf(1.0f + __builtin_amdgcn_exp2f(x * -1.4426950408889634f)); }
;     __device__ __forceinline__ void operator()(const f32x4 (&acc)[2][2][4][2], const Unit& u, int wr, int wc, int fr, int fq, const PG8_LAS float* rtab) const {
;         const int row0 = u.pm * BM + wr * 64 + fr, lcol = u.pn * HALF + wc * 32 + 8 * fq;
;         float rs[2][4]; load_rstd(rtab, wr, fr, rs);
;         f32x4 bv[2], bg[2];
; #pragma unroll
;         for (int n = 0; n < 2; ++n) { bv[n] = (MODE == 0) ? *(const f32x4*)(b0 + lcol + 4 * n) : (f32x4){0.f, 0.f, 0.f, 0.f}; bg[n] = (MODE == 0) ? *(const f32x4*)(b1 + lcol + 4 * n) : (f32x4){0.f, 0.f, 0.f, 0.f}; }
; #pragma unroll
;         for (int ai = 0; ai < 2; ++ai)
; #pragma unroll
;             for (int m = 0; m < 4; ++m) { const float r = rs[ai][m]; float o[8];
; #pragma unroll
;                 for (int n = 0; n < 2; ++n) { const f32x4 a = acc[ai][0][m][n] * r + bv[n], g = acc[ai][1][m][n] * r + bg[n];
; #pragma unroll
;                     for (int e = 0; e < 4; ++e) o[4 * n + e] = (MODE == 0) ? a[e] * fast_sigmoid(g[e]) : a[e] * fast_sigmoid(a[e]) * g[e]; }
;                 u32x4 w; w.x = cvt_pk_bf16(o[0], o[1]); w.y = cvt_pk_bf16(o[2], o[3]); w.z = cvt_pk_bf16(o[4], o[5]); w.w = cvt_pk_bf16(o[6], o[7]);
;                 if (MODE == 1) *(u32x4*)(O + tiled_off(row0 + ai * HALF + m * 16, lcol, ldc)) = w;
;                 else *(u32x4*)(O + (size_t)(row0 + ai * HALF + m * 16) * ldc + lcol) = w; }
.LBB0_793:
	s_and_b64 s[98:99], s[4:5], s[2:3]
	s_and_saveexec_b64 s[98:99], s[98:99]
	s_cbranch_execz .Lrt_skip_up0
	v_lshl_or_b32 v176, s54, 8, v208
	v_ashrrev_i32_e32 v177, 31, v176
	v_lshlrev_b64 v[176:177], 6, v[176:177]
	v_lshl_add_u64 v[176:177], s[24:25], 0, v[176:177]
	global_load_dwordx4 v[160:163], v[176:177], off
	global_load_dwordx4 v[164:167], v[176:177], off offset:16
	global_load_dwordx4 v[168:171], v[176:177], off offset:32
	global_load_dwordx4 v[172:175], v[176:177], off offset:48
.Lrt_skip_up0:
	s_mov_b64 exec, s[98:99]
	s_lshl_b32 s53, s61, 10
	s_and_b32 s55, s53, 0x400
	v_add_u32_e32 v130, s55, v146
	ds_read2_b32 v[152:153], v130 offset1:16
	ds_read2_b32 v[140:141], v130 offset0:32 offset1:48
	ds_read2_b32 v[138:139], v130 offset0:128 offset1:144
	ds_read2_b32 v[136:137], v130 offset0:160 offset1:176
	s_waitcnt lgkmcnt(0)
	s_lshl_b32 s53, s60, 8
	s_add_i32 s53, s53, s38
	v_or_b32_e32 v151, s53, v142
	v_mul_f32_e32 v224, 0xbfb8aa3b, v152
	v_mul_f32_e32 v225, v152, v152
	v_mul_f32_e32 v234, v124, v224
	v_mul_f32_e32 v235, v125, v224
	v_mul_f32_e32 v236, v126, v224
	v_mul_f32_e32 v237, v127, v224
	v_mul_f32_e32 v238, v116, v224
	v_mul_f32_e32 v239, v117, v224
	v_mul_f32_e32 v240, v118, v224
	v_mul_f32_e32 v241, v119, v224
	v_mul_f32_e32 v226, v124, v120
	v_mul_f32_e32 v227, v125, v121
	v_mul_f32_e32 v228, v126, v122
	v_mul_f32_e32 v229, v127, v123
	v_mul_f32_e32 v230, v116, v112
	v_mul_f32_e32 v231, v117, v113
	v_mul_f32_e32 v232, v118, v114
	v_mul_f32_e32 v233, v119, v115
	v_exp_f32_e32 v234, v234
	v_exp_f32_e32 v235, v235
	v_exp_f32_e32 v236, v236
	v_exp_f32_e32 v237, v237
	v_exp_f32_e32 v238, v238
	v_exp_f32_e32 v239, v239
	v_exp_f32_e32 v240, v240
	v_exp_f32_e32 v241, v241
	v_mul_f32_e32 v226, v226, v225
	v_mul_f32_e32 v227, v227, v225
	v_mul_f32_e32 v228, v228, v225
	v_mul_f32_e32 v229, v229, v225
	v_mul_f32_e32 v230, v230, v225
	v_mul_f32_e32 v231, v231, v225
	v_mul_f32_e32 v232, v232, v225
	v_mul_f32_e32 v233, v233, v225
	v_add_f32_e32 v234, 1.0, v234
	v_add_f32_e32 v235, 1.0, v235
	v_add_f32_e32 v236, 1.0, v236
	v_add_f32_e32 v237, 1.0, v237
	v_add_f32_e32 v238, 1.0, v238
	v_add_f32_e32 v239, 1.0, v239
	v_add_f32_e32 v240, 1.0, v240
	v_add_f32_e32 v241, 1.0, v241
	v_rcp_f32_e32 v234, v234
	v_rcp_f32_e32 v235, v235
	v_rcp_f32_e32 v236, v236
	v_rcp_f32_e32 v237, v237
	v_rcp_f32_e32 v238, v238
	v_rcp_f32_e32 v239, v239
	v_rcp_f32_e32 v240, v240
	v_rcp_f32_e32 v241, v241
	v_mul_f32_e32 v226, v226, v234
	v_mul_f32_e32 v227, v227, v235
	v_mul_f32_e32 v228, v228, v236
	v_mul_f32_e32 v229, v229, v237
	v_mul_f32_e32 v230, v230, v238
	v_mul_f32_e32 v231, v231, v239
	v_mul_f32_e32 v232, v232, v240
	v_mul_f32_e32 v233, v233, v241
	v_cvt_pk_bf16_f32 v242, v226, v227
	v_cvt_pk_bf16_f32 v243, v228, v229
	v_cvt_pk_bf16_f32 v244, v230, v231
	v_cvt_pk_bf16_f32 v245, v232, v233
	v_lshlrev_b32_e32 v116, 6, v151
	v_and_or_b32 v118, v116, s40, v143
	v_lshlrev_b32_e32 v116, 2, v151
	v_and_b32_e32 v119, 32, v116
	s_lshl_b32 s55, s68, 7
	s_or_b32 s55, s55, s39
	s_ashr_i32 s60, s55, 6
	s_ashr_i32 s55, s53, 7
	s_mul_i32 s55, s55, 44
	s_ashr_i32 s61, s60, 31
	s_ashr_i32 s69, s55, 31
	s_add_u32 s68, s55, s60
	s_addc_u32 s69, s69, s61
	s_lshl_b64 s[68:69], s[68:69], 14
	s_add_u32 s68, s14, s68
	v_bitop3_b32 v120, v118, s42, v119 bitop3:0xde
	s_addc_u32 s69, s15, s69
	global_store_dwordx4 v120, v[242:245], s[68:69]
	s_or_b32 s55, s53, 16
	s_lshr_b32 s55, s55, 3
	s_and_b32 s55, s55, 10
	s_or_b32 s55, s55, s41
	s_lshl_b32 s55, s55, 10
	v_mul_f32_e32 v224, 0xbfb8aa3b, v140
	v_mul_f32_e32 v225, v140, v140
	v_mul_f32_e32 v234, v92, v224
	v_mul_f32_e32 v235, v93, v224
	v_mul_f32_e32 v236, v94, v224
	v_mul_f32_e32 v237, v95, v224
	v_mul_f32_e32 v238, v84, v224
	v_mul_f32_e32 v239, v85, v224
	v_mul_f32_e32 v240, v86, v224
	v_mul_f32_e32 v241, v87, v224
	v_mul_f32_e32 v226, v92, v88
	v_mul_f32_e32 v227, v93, v89
	v_mul_f32_e32 v228, v94, v90
	v_mul_f32_e32 v229, v95, v91
	v_mul_f32_e32 v230, v84, v80
	v_mul_f32_e32 v231, v85, v81
	v_mul_f32_e32 v232, v86, v82
	v_mul_f32_e32 v233, v87, v83
	v_exp_f32_e32 v234, v234
	v_exp_f32_e32 v235, v235
	v_exp_f32_e32 v236, v236
	v_exp_f32_e32 v237, v237
	v_exp_f32_e32 v238, v238
	v_exp_f32_e32 v239, v239
	v_exp_f32_e32 v240, v240
	v_exp_f32_e32 v241, v241
	v_mul_f32_e32 v226, v226, v225
	v_mul_f32_e32 v227, v227, v225
	v_mul_f32_e32 v228, v228, v225
	v_mul_f32_e32 v229, v229, v225
	v_mul_f32_e32 v230, v230, v225
	v_mul_f32_e32 v231, v231, v225
	v_mul_f32_e32 v232, v232, v225
	v_mul_f32_e32 v233, v233, v225
	v_add_f32_e32 v234, 1.0, v234
	v_add_f32_e32 v235, 1.0, v235
	v_add_f32_e32 v236, 1.0, v236
	v_add_f32_e32 v237, 1.0, v237
	v_add_f32_e32 v238, 1.0, v238
	v_add_f32_e32 v239, 1.0, v239
	v_add_f32_e32 v240, 1.0, v240
	v_add_f32_e32 v241, 1.0, v241
	v_rcp_f32_e32 v234, v234
	v_rcp_f32_e32 v235, v235
	v_rcp_f32_e32 v236, v236
	v_rcp_f32_e32 v237, v237
	v_rcp_f32_e32 v238, v238
	v_rcp_f32_e32 v239, v239
	v_rcp_f32_e32 v240, v240
	v_rcp_f32_e32 v241, v241
	v_mul_f32_e32 v226, v226, v234
	v_mul_f32_e32 v227, v227, v235
	v_mul_f32_e32 v228, v228, v236
	v_mul_f32_e32 v229, v229, v237
	v_mul_f32_e32 v230, v230, v238
	v_mul_f32_e32 v231, v231, v239
	v_mul_f32_e32 v232, v232, v240
	v_mul_f32_e32 v233, v233, v241
	v_cvt_pk_bf16_f32 v250, v226, v227
	v_cvt_pk_bf16_f32 v251, v228, v229
	v_cvt_pk_bf16_f32 v252, v230, v231
	v_cvt_pk_bf16_f32 v253, v232, v233
	v_bitop3_b32 v93, v118, s55, v119 bitop3:0xde
	v_mul_f32_e32 v224, 0xbfb8aa3b, v153
	v_mul_f32_e32 v225, v153, v153
	v_mul_f32_e32 v234, v108, v224
	v_mul_f32_e32 v235, v109, v224
	v_mul_f32_e32 v236, v110, v224
	v_mul_f32_e32 v237, v111, v224
	v_mul_f32_e32 v238, v100, v224
; __host__ __device__ __forceinline__ size_t tiled_off(int row, int col, int K) { return ((size_t)(row >> 7) * (K >> 6) + (col >> 6)) * 8192 + (lds_byte(row & 127, col & 63) >> 1); }
; __device__ __forceinline__ unsigned cvt_pk_bf16(float lo, float hi) { unsigned r; asm volatile("v_cvt_pk_bf16_f32 %0, %1, %2" : "=v"(r) : "v"(lo), "v"(hi)); return r; }
; __device__ __forceinline__ float fast_sigmoid(float x) { return __builtin_amdgcn_rcpf(1.0f + __builtin_amdgcn_exp2f(x * -1.4426950408889634f)); }
;     __device__ __forceinline__ void operator()(const f32x4 (&acc)[2][2][4][2], const Unit& u, int wr, int wc, int fr, int fq, const PG8_LAS float* rtab) const {
;     ...
;             for (int m = 0; m < 4; ++m) { const float r = rs[ai][m]; float o[8];
; #pragma unroll
;                 for (int n = 0; n < 2; ++n) { const f32x4 a = acc[ai][0][m][n] * r + bv[n], g = acc[ai][1][m][n] * r + bg[n];
; #pragma unroll
;                     for (int e = 0; e < 4; ++e) o[4 * n + e] = (MODE == 0) ? a[e] * fast_sigmoid(g[e]) : a[e] * fast_sigmoid(a[e]) * g[e]; }
;                 u32x4 w; w.x = cvt_pk_bf16(o[0], o[1]); w.y = cvt_pk_bf16(o[2], o[3]); w.z = cvt_pk_bf16(o[4], o[5]); w.w = cvt_pk_bf16(o[6], o[7]);
;                 if (MODE == 1) *(u32x4*)(O + tiled_off(row0 + ai * HALF + m * 16, lcol, ldc)) = w;
;                 else *(u32x4*)(O + (size_t)(row0 + ai * HALF + m * 16) * ldc + lcol) = w; }
	v_mul_f32_e32 v239, v101, v224
	v_mul_f32_e32 v240, v102, v224
	v_mul_f32_e32 v241, v103, v224
	v_mul_f32_e32 v226, v108, v104
	v_mul_f32_e32 v227, v109, v105
	v_mul_f32_e32 v228, v110, v106
	v_mul_f32_e32 v229, v111, v107
	v_mul_f32_e32 v230, v100, v96
	v_mul_f32_e32 v231, v101, v97
	v_mul_f32_e32 v232, v102, v98
	v_mul_f32_e32 v233, v103, v99
	v_exp_f32_e32 v234, v234
	v_exp_f32_e32 v235, v235
	v_exp_f32_e32 v236, v236
	v_exp_f32_e32 v237, v237
	v_exp_f32_e32 v238, v238
	v_exp_f32_e32 v239, v239
	v_exp_f32_e32 v240, v240
	v_exp_f32_e32 v241, v241
	v_mul_f32_e32 v226, v226, v225
	v_mul_f32_e32 v227, v227, v225
	v_mul_f32_e32 v228, v228, v225
	v_mul_f32_e32 v229, v229, v225
	v_mul_f32_e32 v230, v230, v225
	v_mul_f32_e32 v231, v231, v225
	v_mul_f32_e32 v232, v232, v225
	v_mul_f32_e32 v233, v233, v225
	v_add_f32_e32 v234, 1.0, v234
	v_add_f32_e32 v235, 1.0, v235
	v_add_f32_e32 v236, 1.0, v236
	v_add_f32_e32 v237, 1.0, v237
	v_add_f32_e32 v238, 1.0, v238
	v_add_f32_e32 v239, 1.0, v239
	v_add_f32_e32 v240, 1.0, v240
	v_add_f32_e32 v241, 1.0, v241
	v_rcp_f32_e32 v234, v234
	v_rcp_f32_e32 v235, v235
	v_rcp_f32_e32 v236, v236
	v_rcp_f32_e32 v237, v237
	v_rcp_f32_e32 v238, v238
	v_rcp_f32_e32 v239, v239
	v_rcp_f32_e32 v240, v240
	v_rcp_f32_e32 v241, v241
	v_mul_f32_e32 v226, v226, v234
	v_mul_f32_e32 v227, v227, v235
	v_mul_f32_e32 v228, v228, v236
	v_mul_f32_e32 v229, v229, v237
	v_mul_f32_e32 v230, v230, v238
	v_mul_f32_e32 v231, v231, v239
	v_mul_f32_e32 v232, v232, v240
	v_mul_f32_e32 v233, v233, v241
	v_cvt_pk_bf16_f32 v246, v226, v227
	v_cvt_pk_bf16_f32 v247, v228, v229
	v_cvt_pk_bf16_f32 v248, v230, v231
	v_cvt_pk_bf16_f32 v249, v232, v233
	global_store_dwordx4 v93, v[246:249], s[68:69]
	s_or_b32 s55, s53, 32
	s_lshr_b32 s55, s55, 3
	s_and_b32 s55, s55, 12
	s_or_b32 s55, s55, s41
	s_lshl_b32 s55, s55, 10
	v_bitop3_b32 v87, v118, s55, v119 bitop3:0xde
	global_store_dwordx4 v87, v[250:253], s[68:69]
	s_or_b32 s53, s53, 48
	s_lshr_b32 s53, s53, 3
	s_and_b32 s53, s53, 14
	s_or_b32 s53, s53, s41
	s_lshl_b32 s53, s53, 10
	v_mul_f32_e32 v224, 0xbfb8aa3b, v141
	v_mul_f32_e32 v225, v141, v141
	v_mul_f32_e32 v234, v76, v224
	v_mul_f32_e32 v235, v77, v224
	v_mul_f32_e32 v236, v78, v224
	v_mul_f32_e32 v237, v79, v224
	v_mul_f32_e32 v238, v68, v224
	v_mul_f32_e32 v239, v69, v224
	v_mul_f32_e32 v240, v70, v224
	v_mul_f32_e32 v241, v71, v224
	v_mul_f32_e32 v226, v76, v72
	v_mul_f32_e32 v227, v77, v73
	v_mul_f32_e32 v228, v78, v74
	v_mul_f32_e32 v229, v79, v75
	v_mul_f32_e32 v230, v68, v64
	v_mul_f32_e32 v231, v69, v65
	v_mul_f32_e32 v232, v70, v66
	v_mul_f32_e32 v233, v71, v67
	v_exp_f32_e32 v234, v234
	v_exp_f32_e32 v235, v235
	v_exp_f32_e32 v236, v236
	v_exp_f32_e32 v237, v237
	v_exp_f32_e32 v238, v238
	v_exp_f32_e32 v239, v239
	v_exp_f32_e32 v240, v240
	v_exp_f32_e32 v241, v241
	v_mul_f32_e32 v226, v226, v225
	v_mul_f32_e32 v227, v227, v225
	v_mul_f32_e32 v228, v228, v225
	v_mul_f32_e32 v229, v229, v225
	v_mul_f32_e32 v230, v230, v225
	v_mul_f32_e32 v231, v231, v225
	v_mul_f32_e32 v232, v232, v225
	v_mul_f32_e32 v233, v233, v225
	v_add_f32_e32 v234, 1.0, v234
	v_add_f32_e32 v235, 1.0, v235
	v_add_f32_e32 v236, 1.0, v236
	v_add_f32_e32 v237, 1.0, v237
	v_add_f32_e32 v238, 1.0, v238
	v_add_f32_e32 v239, 1.0, v239
	v_add_f32_e32 v240, 1.0, v240
	v_add_f32_e32 v241, 1.0, v241
	v_rcp_f32_e32 v234, v234
	v_rcp_f32_e32 v235, v235
	v_rcp_f32_e32 v236, v236
	v_rcp_f32_e32 v237, v237
	v_rcp_f32_e32 v238, v238
	v_rcp_f32_e32 v239, v239
	v_rcp_f32_e32 v240, v240
	v_rcp_f32_e32 v241, v241
	v_mul_f32_e32 v226, v226, v234
	v_mul_f32_e32 v227, v227, v235
	v_mul_f32_e32 v228, v228, v236
	v_mul_f32_e32 v229, v229, v237
	v_mul_f32_e32 v230, v230, v238
	v_mul_f32_e32 v231, v231, v239
	v_mul_f32_e32 v232, v232, v240
	v_mul_f32_e32 v233, v233, v241
	v_cvt_pk_bf16_f32 v242, v226, v227
	v_cvt_pk_bf16_f32 v243, v228, v229
	v_cvt_pk_bf16_f32 v244, v230, v231
	v_cvt_pk_bf16_f32 v245, v232, v233
	v_bitop3_b32 v68, v118, s53, v119 bitop3:0xde
	global_store_dwordx4 v68, v[242:245], s[68:69]
	s_andn2_b64 vcc, exec, s[4:5]
	s_mov_b64 s[4:5], -1
	v_add_u32_e32 v67, 0x80, v151
	v_ashrrev_i32_e32 v66, 7, v67
	v_mul_f32_e32 v224, 0xbfb8aa3b, v138
	v_mul_f32_e32 v225, v138, v138
	v_mul_f32_e32 v234, v60, v224
	v_mul_f32_e32 v235, v61, v224
	v_mul_f32_e32 v236, v62, v224
	v_mul_f32_e32 v237, v63, v224
	v_mul_f32_e32 v238, v52, v224
	v_mul_f32_e32 v239, v53, v224
	v_mul_f32_e32 v240, v54, v224
	v_mul_f32_e32 v241, v55, v224
	v_mul_f32_e32 v226, v60, v56
	v_mul_f32_e32 v227, v61, v57
	v_mul_f32_e32 v228, v62, v58
	v_mul_f32_e32 v229, v63, v59
	v_mul_f32_e32 v230, v52, v48
	v_mul_f32_e32 v231, v53, v49
	v_mul_f32_e32 v232, v54, v50
	v_mul_f32_e32 v233, v55, v51
	v_exp_f32_e32 v234, v234
	v_exp_f32_e32 v235, v235
	v_exp_f32_e32 v236, v236
	v_exp_f32_e32 v237, v237
	v_exp_f32_e32 v238, v238
	v_exp_f32_e32 v239, v239
	v_exp_f32_e32 v240, v240
	v_exp_f32_e32 v241, v241
	v_mul_f32_e32 v226, v226, v225
	v_mul_f32_e32 v227, v227, v225
	v_mul_f32_e32 v228, v228, v225
	v_mul_f32_e32 v229, v229, v225
	v_mul_f32_e32 v230, v230, v225
	v_mul_f32_e32 v231, v231, v225
	v_mul_f32_e32 v232, v232, v225
	v_mul_f32_e32 v233, v233, v225
	v_add_f32_e32 v234, 1.0, v234
	v_add_f32_e32 v235, 1.0, v235
	v_add_f32_e32 v236, 1.0, v236
	v_add_f32_e32 v237, 1.0, v237
	v_add_f32_e32 v238, 1.0, v238
	v_add_f32_e32 v239, 1.0, v239
	v_add_f32_e32 v240, 1.0, v240
	v_add_f32_e32 v241, 1.0, v241
	v_rcp_f32_e32 v234, v234
	v_rcp_f32_e32 v235, v235
	v_rcp_f32_e32 v236, v236
	v_rcp_f32_e32 v237, v237
	v_rcp_f32_e32 v238, v238
	v_rcp_f32_e32 v239, v239
	v_rcp_f32_e32 v240, v240
	v_rcp_f32_e32 v241, v241
	v_mul_f32_e32 v226, v226, v234
; __host__ __device__ __forceinline__ size_t tiled_off(int row, int col, int K) { return ((size_t)(row >> 7) * (K >> 6) + (col >> 6)) * 8192 + (lds_byte(row & 127, col & 63) >> 1); }
; __device__ __forceinline__ unsigned cvt_pk_bf16(float lo, float hi) { unsigned r; asm volatile("v_cvt_pk_bf16_f32 %0, %1, %2" : "=v"(r) : "v"(lo), "v"(hi)); return r; }
; __device__ __forceinline__ float fast_sigmoid(float x) { return __builtin_amdgcn_rcpf(1.0f + __builtin_amdgcn_exp2f(x * -1.4426950408889634f)); }
;     __device__ __forceinline__ void operator()(const f32x4 (&acc)[2][2][4][2], const Unit& u, int wr, int wc, int fr, int fq, const PG8_LAS float* rtab) const {
;     ...
;             for (int m = 0; m < 4; ++m) { const float r = rs[ai][m]; float o[8];
; #pragma unroll
;                 for (int n = 0; n < 2; ++n) { const f32x4 a = acc[ai][0][m][n] * r + bv[n], g = acc[ai][1][m][n] * r + bg[n];
; #pragma unroll
;                     for (int e = 0; e < 4; ++e) o[4 * n + e] = (MODE == 0) ? a[e] * fast_sigmoid(g[e]) : a[e] * fast_sigmoid(a[e]) * g[e]; }
;                 u32x4 w; w.x = cvt_pk_bf16(o[0], o[1]); w.y = cvt_pk_bf16(o[2], o[3]); w.z = cvt_pk_bf16(o[4], o[5]); w.w = cvt_pk_bf16(o[6], o[7]);
;                 if (MODE == 1) *(u32x4*)(O + tiled_off(row0 + ai * HALF + m * 16, lcol, ldc)) = w;
;                 else *(u32x4*)(O + (size_t)(row0 + ai * HALF + m * 16) * ldc + lcol) = w; }
	v_mul_f32_e32 v227, v227, v235
	v_mul_f32_e32 v228, v228, v236
	v_mul_f32_e32 v229, v229, v237
	v_mul_f32_e32 v230, v230, v238
	v_mul_f32_e32 v231, v231, v239
	v_mul_f32_e32 v232, v232, v240
	v_mul_f32_e32 v233, v233, v241
	v_cvt_pk_bf16_f32 v246, v226, v227
	v_cvt_pk_bf16_f32 v247, v228, v229
	v_cvt_pk_bf16_f32 v248, v230, v231
	v_cvt_pk_bf16_f32 v249, v232, v233
	v_lshlrev_b32_e32 v55, 2, v67
	v_and_b32_e32 v55, 32, v55
	v_lshlrev_b32_e32 v54, 6, v67
	v_and_or_b32 v54, v54, s40, v143
	v_bitop3_b32 v130, v54, s42, v55 bitop3:0xde
	v_mul_lo_u32 v48, v66, 44
	v_ashrrev_i32_e32 v49, 31, v48
	v_lshl_add_u64 v[48:49], v[48:49], 0, s[60:61]
	v_lshlrev_b64 v[48:49], 14, v[48:49]
	v_lshl_add_u64 v[48:49], s[14:15], 0, v[48:49]
	v_lshl_add_u64 v[56:57], v[48:49], 0, v[130:131]
	global_store_dwordx4 v[56:57], v[246:249], off
	s_nop 0
	v_mul_f32_e32 v224, 0xbfb8aa3b, v139
	v_mul_f32_e32 v225, v139, v139
	v_mul_f32_e32 v234, v44, v224
	v_mul_f32_e32 v235, v45, v224
	v_mul_f32_e32 v236, v46, v224
	v_mul_f32_e32 v237, v47, v224
	v_mul_f32_e32 v238, v36, v224
	v_mul_f32_e32 v239, v37, v224
	v_mul_f32_e32 v240, v38, v224
	v_mul_f32_e32 v241, v39, v224
	v_mul_f32_e32 v226, v44, v40
	v_mul_f32_e32 v227, v45, v41
	v_mul_f32_e32 v228, v46, v42
	v_mul_f32_e32 v229, v47, v43
	v_mul_f32_e32 v230, v36, v32
	v_mul_f32_e32 v231, v37, v33
	v_mul_f32_e32 v232, v38, v34
	v_mul_f32_e32 v233, v39, v35
	v_exp_f32_e32 v234, v234
	v_exp_f32_e32 v235, v235
	v_exp_f32_e32 v236, v236
	v_exp_f32_e32 v237, v237
	v_exp_f32_e32 v238, v238
	v_exp_f32_e32 v239, v239
	v_exp_f32_e32 v240, v240
	v_exp_f32_e32 v241, v241
	v_mul_f32_e32 v226, v226, v225
	v_mul_f32_e32 v227, v227, v225
	v_mul_f32_e32 v228, v228, v225
	v_mul_f32_e32 v229, v229, v225
	v_mul_f32_e32 v230, v230, v225
	v_mul_f32_e32 v231, v231, v225
	v_mul_f32_e32 v232, v232, v225
	v_mul_f32_e32 v233, v233, v225
	v_add_f32_e32 v234, 1.0, v234
	v_add_f32_e32 v235, 1.0, v235
	v_add_f32_e32 v236, 1.0, v236
	v_add_f32_e32 v237, 1.0, v237
	v_add_f32_e32 v238, 1.0, v238
	v_add_f32_e32 v239, 1.0, v239
	v_add_f32_e32 v240, 1.0, v240
	v_add_f32_e32 v241, 1.0, v241
	v_rcp_f32_e32 v234, v234
	v_rcp_f32_e32 v235, v235
	v_rcp_f32_e32 v236, v236
	v_rcp_f32_e32 v237, v237
	v_rcp_f32_e32 v238, v238
	v_rcp_f32_e32 v239, v239
	v_rcp_f32_e32 v240, v240
	v_rcp_f32_e32 v241, v241
	v_mul_f32_e32 v226, v226, v234
	v_mul_f32_e32 v227, v227, v235
	v_mul_f32_e32 v228, v228, v236
	v_mul_f32_e32 v229, v229, v237
	v_mul_f32_e32 v230, v230, v238
	v_mul_f32_e32 v231, v231, v239
	v_mul_f32_e32 v232, v232, v240
	v_mul_f32_e32 v233, v233, v241
	v_cvt_pk_bf16_f32 v250, v226, v227
	v_cvt_pk_bf16_f32 v251, v228, v229
	v_cvt_pk_bf16_f32 v252, v230, v231
	v_cvt_pk_bf16_f32 v253, v232, v233
	v_add_u32_e32 v36, 0x90, v151
	v_lshrrev_b32_e32 v37, 3, v36
	v_and_or_b32 v37, v37, 10, s41
	v_lshlrev_b32_e32 v38, 6, v36
	v_lshlrev_b32_e32 v36, 2, v36
	v_and_or_b32 v38, v38, s40, v143
	v_lshlrev_b32_e32 v37, 10, v37
	v_and_b32_e32 v36, 32, v36
	v_bitop3_b32 v130, v38, v37, v36 bitop3:0xde
	v_mul_f32_e32 v224, 0xbfb8aa3b, v136
	v_mul_f32_e32 v225, v136, v136
	v_mul_f32_e32 v234, v28, v224
	v_mul_f32_e32 v235, v29, v224
	v_mul_f32_e32 v236, v30, v224
	v_mul_f32_e32 v237, v31, v224
	v_mul_f32_e32 v238, v20, v224
	v_mul_f32_e32 v239, v21, v224
	v_mul_f32_e32 v240, v22, v224
	v_mul_f32_e32 v241, v23, v224
	v_mul_f32_e32 v226, v28, v24
	v_mul_f32_e32 v227, v29, v25
	v_mul_f32_e32 v228, v30, v26
	v_mul_f32_e32 v229, v31, v27
	v_mul_f32_e32 v230, v20, v16
	v_mul_f32_e32 v231, v21, v17
	v_mul_f32_e32 v232, v22, v18
	v_mul_f32_e32 v233, v23, v19
	v_exp_f32_e32 v234, v234
	v_exp_f32_e32 v235, v235
	v_exp_f32_e32 v236, v236
	v_exp_f32_e32 v237, v237
	v_exp_f32_e32 v238, v238
	v_exp_f32_e32 v239, v239
	v_exp_f32_e32 v240, v240
	v_exp_f32_e32 v241, v241
	v_mul_f32_e32 v226, v226, v225
	v_mul_f32_e32 v227, v227, v225
	v_mul_f32_e32 v228, v228, v225
	v_mul_f32_e32 v229, v229, v225
	v_mul_f32_e32 v230, v230, v225
	v_mul_f32_e32 v231, v231, v225
	v_mul_f32_e32 v232, v232, v225
	v_mul_f32_e32 v233, v233, v225
	v_add_f32_e32 v234, 1.0, v234
	v_add_f32_e32 v235, 1.0, v235
	v_add_f32_e32 v236, 1.0, v236
	v_add_f32_e32 v237, 1.0, v237
; __host__ __device__ __forceinline__ size_t tiled_off(int row, int col, int K) { return ((size_t)(row >> 7) * (K >> 6) + (col >> 6)) * 8192 + (lds_byte(row & 127, col & 63) >> 1); }
; __device__ __forceinline__ unsigned cvt_pk_bf16(float lo, float hi) { unsigned r; asm volatile("v_cvt_pk_bf16_f32 %0, %1, %2" : "=v"(r) : "v"(lo), "v"(hi)); return r; }
; __device__ __forceinline__ float fast_sigmoid(float x) { return __builtin_amdgcn_rcpf(1.0f + __builtin_amdgcn_exp2f(x * -1.4426950408889634f)); }
;     __device__ __forceinline__ void operator()(const f32x4 (&acc)[2][2][4][2], const Unit& u, int wr, int wc, int fr, int fq, const PG8_LAS float* rtab) const {
;     ...
;             for (int m = 0; m < 4; ++m) { const float r = rs[ai][m]; float o[8];
; #pragma unroll
;                 for (int n = 0; n < 2; ++n) { const f32x4 a = acc[ai][0][m][n] * r + bv[n], g = acc[ai][1][m][n] * r + bg[n];
; #pragma unroll
;                     for (int e = 0; e < 4; ++e) o[4 * n + e] = (MODE == 0) ? a[e] * fast_sigmoid(g[e]) : a[e] * fast_sigmoid(a[e]) * g[e]; }
;                 u32x4 w; w.x = cvt_pk_bf16(o[0], o[1]); w.y = cvt_pk_bf16(o[2], o[3]); w.z = cvt_pk_bf16(o[4], o[5]); w.w = cvt_pk_bf16(o[6], o[7]);
;                 if (MODE == 1) *(u32x4*)(O + tiled_off(row0 + ai * HALF + m * 16, lcol, ldc)) = w;
;                 else *(u32x4*)(O + (size_t)(row0 + ai * HALF + m * 16) * ldc + lcol) = w; }
	v_add_f32_e32 v238, 1.0, v238
	v_add_f32_e32 v239, 1.0, v239
	v_add_f32_e32 v240, 1.0, v240
	v_add_f32_e32 v241, 1.0, v241
	v_rcp_f32_e32 v234, v234
	v_rcp_f32_e32 v235, v235
	v_rcp_f32_e32 v236, v236
	v_rcp_f32_e32 v237, v237
	v_rcp_f32_e32 v238, v238
	v_rcp_f32_e32 v239, v239
	v_rcp_f32_e32 v240, v240
	v_rcp_f32_e32 v241, v241
	v_mul_f32_e32 v226, v226, v234
	v_mul_f32_e32 v227, v227, v235
	v_mul_f32_e32 v228, v228, v236
	v_mul_f32_e32 v229, v229, v237
	v_mul_f32_e32 v230, v230, v238
	v_mul_f32_e32 v231, v231, v239
	v_mul_f32_e32 v232, v232, v240
	v_mul_f32_e32 v233, v233, v241
	v_cvt_pk_bf16_f32 v242, v226, v227
	v_cvt_pk_bf16_f32 v243, v228, v229
	v_cvt_pk_bf16_f32 v244, v230, v231
	v_cvt_pk_bf16_f32 v245, v232, v233
	v_lshl_add_u64 v[28:29], v[48:49], 0, v[130:131]
	global_store_dwordx4 v[28:29], v[250:253], off
	v_add_u32_e32 v20, 0xa0, v151
	v_lshrrev_b32_e32 v21, 3, v20
	v_and_or_b32 v21, v21, 12, s41
	v_lshlrev_b32_e32 v22, 6, v20
	v_lshlrev_b32_e32 v20, 2, v20
	v_and_or_b32 v22, v22, s40, v143
	v_lshlrev_b32_e32 v21, 10, v21
	v_and_b32_e32 v20, 32, v20
	v_bitop3_b32 v130, v22, v21, v20 bitop3:0xde
	v_lshl_add_u64 v[22:23], v[48:49], 0, v[130:131]
	global_store_dwordx4 v[22:23], v[242:245], off
	v_mul_f32_e32 v224, 0xbfb8aa3b, v137
	v_mul_f32_e32 v225, v137, v137
	v_mul_f32_e32 v234, v12, v224
	v_mul_f32_e32 v235, v13, v224
	v_mul_f32_e32 v236, v14, v224
	v_mul_f32_e32 v237, v15, v224
	v_mul_f32_e32 v238, v4, v224
	v_mul_f32_e32 v239, v5, v224
	v_mul_f32_e32 v240, v6, v224
	v_mul_f32_e32 v241, v7, v224
	v_mul_f32_e32 v226, v12, v8
	v_mul_f32_e32 v227, v13, v9
	v_mul_f32_e32 v228, v14, v10
	v_mul_f32_e32 v229, v15, v11
	v_mul_f32_e32 v230, v4, v0
	v_mul_f32_e32 v231, v5, v1
	v_mul_f32_e32 v232, v6, v2
	v_mul_f32_e32 v233, v7, v3
	v_exp_f32_e32 v234, v234
	v_exp_f32_e32 v235, v235
	v_exp_f32_e32 v236, v236
	v_exp_f32_e32 v237, v237
	v_exp_f32_e32 v238, v238
	v_exp_f32_e32 v239, v239
	v_exp_f32_e32 v240, v240
	v_exp_f32_e32 v241, v241
	v_mul_f32_e32 v226, v226, v225
	v_mul_f32_e32 v227, v227, v225
	v_mul_f32_e32 v228, v228, v225
	v_mul_f32_e32 v229, v229, v225
	v_mul_f32_e32 v230, v230, v225
	v_mul_f32_e32 v231, v231, v225
	v_mul_f32_e32 v232, v232, v225
	v_mul_f32_e32 v233, v233, v225
	v_add_f32_e32 v234, 1.0, v234
	v_add_f32_e32 v235, 1.0, v235
	v_add_f32_e32 v236, 1.0, v236
	v_add_f32_e32 v237, 1.0, v237
	v_add_f32_e32 v238, 1.0, v238
	v_add_f32_e32 v239, 1.0, v239
	v_add_f32_e32 v240, 1.0, v240
	v_add_f32_e32 v241, 1.0, v241
	v_rcp_f32_e32 v234, v234
	v_rcp_f32_e32 v235, v235
	v_rcp_f32_e32 v236, v236
	v_rcp_f32_e32 v237, v237
	v_rcp_f32_e32 v238, v238
	v_rcp_f32_e32 v239, v239
	v_rcp_f32_e32 v240, v240
	v_rcp_f32_e32 v241, v241
	v_mul_f32_e32 v226, v226, v234
	v_mul_f32_e32 v227, v227, v235
	v_mul_f32_e32 v228, v228, v236
	v_mul_f32_e32 v229, v229, v237
	v_mul_f32_e32 v230, v230, v238
	v_mul_f32_e32 v231, v231, v239
	v_mul_f32_e32 v232, v232, v240
	v_mul_f32_e32 v233, v233, v241
	v_cvt_pk_bf16_f32 v246, v226, v227
	v_cvt_pk_bf16_f32 v247, v228, v229
	v_cvt_pk_bf16_f32 v248, v230, v231
	v_cvt_pk_bf16_f32 v249, v232, v233
	v_add_u32_e32 v4, 0xb0, v151
	v_lshrrev_b32_e32 v5, 3, v4
	v_and_or_b32 v5, v5, 14, s41
	v_lshlrev_b32_e32 v6, 6, v4
	v_lshlrev_b32_e32 v4, 2, v4
	v_and_or_b32 v6, v6, s40, v143
	v_lshlrev_b32_e32 v5, 10, v5
	v_and_b32_e32 v4, 32, v4
	v_bitop3_b32 v130, v6, v5, v4 bitop3:0xde
	v_lshl_add_u64 v[4:5], v[48:49], 0, v[130:131]
	global_store_dwordx4 v[4:5], v[246:249], off
	s_cbranch_vccnz .LBB0_786
	s_and_saveexec_b64 s[4:5], s[2:3]
	s_cbranch_execz .LBB0_796
	s_lshl_b32 s53, s78, 10
	s_and_b32 s53, s53, 0x400
	s_waitcnt vmcnt(8)
	v_pk_add_f32 v[2:3], v[162:163], v[166:167]
	v_pk_add_f32 v[0:1], v[160:161], v[164:165]
	v_pk_add_f32 v[4:5], v[170:171], v[174:175]
	v_pk_add_f32 v[6:7], v[168:169], v[172:173]
	v_pk_add_f32 v[2:3], v[2:3], v[4:5]
	v_pk_add_f32 v[0:1], v[0:1], v[6:7]
	s_nop 0
	v_pk_mov_b32 v[4:5], v[0:1], v[2:3] op_sel:[1,0]
	v_mov_b32_e32 v1, v3
	v_pk_add_f32 v[0:1], v[4:5], v[0:1]
	s_nop 0
	v_add_f32_e32 v0, v0, v1
	v_fmamk_f32 v0, v0, 0x3a800000, v150
	v_rsq_f32_e32 v0, v0
	v_add_u32_e32 v1, s53, v145
	ds_write_b32 v1, v0

; #define PG8_LAS __attribute__((address_space(3)))
; __host__ __device__ __forceinline__ size_t tiled_off(int row, int col, int K) { return ((size_t)(row >> 7) * (K >> 6) + (col >> 6)) * 8192 + (lds_byte(row & 127, col & 63) >> 1); }
; __device__ __forceinline__ unsigned cvt_pk_bf16(float lo, float hi) { unsigned r; asm volatile("v_cvt_pk_bf16_f32 %0, %1, %2" : "=v"(r) : "v"(lo), "v"(hi)); return r; }
; __device__ __forceinline__ float fast_sigmoid(float x) { return __builtin_amdgcn_rcpf(1.0f + __builtin_amdgcn_exp2f(x * -1.4426950408889634f)); }
;     __device__ __forceinline__ void operator()(const f32x4 (&acc)[2][2][4][2], const Unit& u, int wr, int wc, int fr, int fq, const PG8_LAS float* rtab) const {
;         const int row0 = u.pm * BM + wr * 64 + fr, lcol = u.pn * HALF + wc * 32 + 8 * fq;
;         float rs[2][4]; load_rstd(rtab, wr, fr, rs);
;         f32x4 bv[2], bg[2];
; #pragma unroll
;         for (int n = 0; n < 2; ++n) { bv[n] = (MODE == 0) ? *(const f32x4*)(b0 + lcol + 4 * n) : (f32x4){0.f, 0.f, 0.f, 0.f}; bg[n] = (MODE == 0) ? *(const f32x4*)(b1 + lcol + 4 * n) : (f32x4){0.f, 0.f, 0.f, 0.f}; }
; #pragma unroll
;         for (int ai = 0; ai < 2; ++ai)
; #pragma unroll
;             for (int m = 0; m < 4; ++m) { const float r = rs[ai][m]; float o[8];
; #pragma unroll
;                 for (int n = 0; n < 2; ++n) { const f32x4 a = acc[ai][0][m][n] * r + bv[n], g = acc[ai][1][m][n] * r + bg[n];
; #pragma unroll
;                     for (int e = 0; e < 4; ++e) o[4 * n + e] = (MODE == 0) ? a[e] * fast_sigmoid(g[e]) : a[e] * fast_sigmoid(a[e]) * g[e]; }
;                 u32x4 w; w.x = cvt_pk_bf16(o[0], o[1]); w.y = cvt_pk_bf16(o[2], o[3]); w.z = cvt_pk_bf16(o[4], o[5]); w.w = cvt_pk_bf16(o[6], o[7]);
;                 if (MODE == 1) *(u32x4*)(O + tiled_off(row0 + ai * HALF + m * 16, lcol, ldc)) = w;
;                 else *(u32x4*)(O + (size_t)(row0 + ai * HALF + m * 16) * ldc + lcol) = w; }
.LBB0_1628:
	s_and_b64 s[98:99], s[4:5], s[2:3]
	s_and_saveexec_b64 s[98:99], s[98:99]
	s_cbranch_execz .Lrt_skip_up1
	v_lshl_or_b32 v176, s46, 8, v208
	v_ashrrev_i32_e32 v177, 31, v176
	v_lshlrev_b64 v[176:177], 6, v[176:177]
	v_lshl_add_u64 v[176:177], s[10:11], 0, v[176:177]
	global_load_dwordx4 v[160:163], v[176:177], off
	global_load_dwordx4 v[164:167], v[176:177], off offset:16
	global_load_dwordx4 v[168:171], v[176:177], off offset:32
	global_load_dwordx4 v[172:175], v[176:177], off offset:48
.Lrt_skip_up1:
	s_mov_b64 exec, s[98:99]
	s_lshl_b32 s45, s53, 10
	s_and_b32 s47, s45, 0x400
	v_add_u32_e32 v130, s47, v146
	ds_read2_b32 v[152:153], v130 offset1:16
	ds_read2_b32 v[140:141], v130 offset0:32 offset1:48
	ds_read2_b32 v[138:139], v130 offset0:128 offset1:144
	ds_read2_b32 v[136:137], v130 offset0:160 offset1:176
	s_waitcnt lgkmcnt(0)
	s_lshl_b32 s45, s52, 8
	s_add_i32 s45, s45, s62
	v_or_b32_e32 v151, s45, v142
	v_mul_f32_e32 v224, 0xbfb8aa3b, v152
	v_mul_f32_e32 v225, v152, v152
	v_mul_f32_e32 v234, v124, v224
	v_mul_f32_e32 v235, v125, v224
	v_mul_f32_e32 v236, v126, v224
	v_mul_f32_e32 v237, v127, v224
	v_mul_f32_e32 v238, v116, v224
	v_mul_f32_e32 v239, v117, v224
	v_mul_f32_e32 v240, v118, v224
	v_mul_f32_e32 v241, v119, v224
	v_mul_f32_e32 v226, v124, v120
	v_mul_f32_e32 v227, v125, v121
	v_mul_f32_e32 v228, v126, v122
	v_mul_f32_e32 v229, v127, v123
	v_mul_f32_e32 v230, v116, v112
	v_mul_f32_e32 v231, v117, v113
	v_mul_f32_e32 v232, v118, v114
	v_mul_f32_e32 v233, v119, v115
	v_exp_f32_e32 v234, v234
	v_exp_f32_e32 v235, v235
	v_exp_f32_e32 v236, v236
	v_exp_f32_e32 v237, v237
	v_exp_f32_e32 v238, v238
	v_exp_f32_e32 v239, v239
	v_exp_f32_e32 v240, v240
	v_exp_f32_e32 v241, v241
	v_mul_f32_e32 v226, v226, v225
	v_mul_f32_e32 v227, v227, v225
	v_mul_f32_e32 v228, v228, v225
	v_mul_f32_e32 v229, v229, v225
	v_mul_f32_e32 v230, v230, v225
	v_mul_f32_e32 v231, v231, v225
	v_mul_f32_e32 v232, v232, v225
	v_mul_f32_e32 v233, v233, v225
	v_add_f32_e32 v234, 1.0, v234
	v_add_f32_e32 v235, 1.0, v235
	v_add_f32_e32 v236, 1.0, v236
	v_add_f32_e32 v237, 1.0, v237
	v_add_f32_e32 v238, 1.0, v238
	v_add_f32_e32 v239, 1.0, v239
	v_add_f32_e32 v240, 1.0, v240
	v_add_f32_e32 v241, 1.0, v241
	v_rcp_f32_e32 v234, v234
	v_rcp_f32_e32 v235, v235
	v_rcp_f32_e32 v236, v236
	v_rcp_f32_e32 v237, v237
	v_rcp_f32_e32 v238, v238
	v_rcp_f32_e32 v239, v239
	v_rcp_f32_e32 v240, v240
	v_rcp_f32_e32 v241, v241
	v_mul_f32_e32 v226, v226, v234
	v_mul_f32_e32 v227, v227, v235
	v_mul_f32_e32 v228, v228, v236
	v_mul_f32_e32 v229, v229, v237
	v_mul_f32_e32 v230, v230, v238
	v_mul_f32_e32 v231, v231, v239
	v_mul_f32_e32 v232, v232, v240
	v_mul_f32_e32 v233, v233, v241
	v_cvt_pk_bf16_f32 v242, v226, v227
	v_cvt_pk_bf16_f32 v243, v228, v229
	v_cvt_pk_bf16_f32 v244, v230, v231
	v_cvt_pk_bf16_f32 v245, v232, v233
	v_lshlrev_b32_e32 v116, 6, v151
	v_and_or_b32 v118, v116, s64, v143
	v_lshlrev_b32_e32 v116, 2, v151
	v_and_b32_e32 v119, 32, v116
	s_lshl_b32 s47, s54, 7
	s_or_b32 s47, s47, s63
	s_ashr_i32 s52, s47, 6
	s_ashr_i32 s47, s45, 7
	s_mul_i32 s47, s47, 44
	s_ashr_i32 s53, s52, 31
	s_ashr_i32 s55, s47, 31
	s_add_u32 s54, s47, s52
	s_addc_u32 s55, s55, s53
	s_lshl_b64 s[54:55], s[54:55], 14
	s_add_u32 s54, s24, s54
	v_bitop3_b32 v120, v118, s66, v119 bitop3:0xde
	s_addc_u32 s55, s25, s55
	global_store_dwordx4 v120, v[242:245], s[54:55]
	s_or_b32 s47, s45, 16
	s_lshr_b32 s47, s47, 3
	s_and_b32 s47, s47, 10
	s_or_b32 s47, s47, s65
	s_lshl_b32 s47, s47, 10
	v_mul_f32_e32 v224, 0xbfb8aa3b, v140
	v_mul_f32_e32 v225, v140, v140
	v_mul_f32_e32 v234, v92, v224
	v_mul_f32_e32 v235, v93, v224
	v_mul_f32_e32 v236, v94, v224
	v_mul_f32_e32 v237, v95, v224
	v_mul_f32_e32 v238, v84, v224
	v_mul_f32_e32 v239, v85, v224
	v_mul_f32_e32 v240, v86, v224
	v_mul_f32_e32 v241, v87, v224
	v_mul_f32_e32 v226, v92, v88
	v_mul_f32_e32 v227, v93, v89
	v_mul_f32_e32 v228, v94, v90
	v_mul_f32_e32 v229, v95, v91
	v_mul_f32_e32 v230, v84, v80
	v_mul_f32_e32 v231, v85, v81
	v_mul_f32_e32 v232, v86, v82
	v_mul_f32_e32 v233, v87, v83
	v_exp_f32_e32 v234, v234
	v_exp_f32_e32 v235, v235
	v_exp_f32_e32 v236, v236
	v_exp_f32_e32 v237, v237
	v_exp_f32_e32 v238, v238
	v_exp_f32_e32 v239, v239
	v_exp_f32_e32 v240, v240
	v_exp_f32_e32 v241, v241
	v_mul_f32_e32 v226, v226, v225
	v_mul_f32_e32 v227, v227, v225
	v_mul_f32_e32 v228, v228, v225
	v_mul_f32_e32 v229, v229, v225
	v_mul_f32_e32 v230, v230, v225
	v_mul_f32_e32 v231, v231, v225
	v_mul_f32_e32 v232, v232, v225
	v_mul_f32_e32 v233, v233, v225
	v_add_f32_e32 v234, 1.0, v234
	v_add_f32_e32 v235, 1.0, v235
	v_add_f32_e32 v236, 1.0, v236
	v_add_f32_e32 v237, 1.0, v237
	v_add_f32_e32 v238, 1.0, v238
	v_add_f32_e32 v239, 1.0, v239
	v_add_f32_e32 v240, 1.0, v240
	v_add_f32_e32 v241, 1.0, v241
	v_rcp_f32_e32 v234, v234
	v_rcp_f32_e32 v235, v235
	v_rcp_f32_e32 v236, v236
	v_rcp_f32_e32 v237, v237
	v_rcp_f32_e32 v238, v238
	v_rcp_f32_e32 v239, v239
	v_rcp_f32_e32 v240, v240
	v_rcp_f32_e32 v241, v241
	v_mul_f32_e32 v226, v226, v234
	v_mul_f32_e32 v227, v227, v235
	v_mul_f32_e32 v228, v228, v236
	v_mul_f32_e32 v229, v229, v237
	v_mul_f32_e32 v230, v230, v238
	v_mul_f32_e32 v231, v231, v239
	v_mul_f32_e32 v232, v232, v240
	v_mul_f32_e32 v233, v233, v241
	v_cvt_pk_bf16_f32 v250, v226, v227
	v_cvt_pk_bf16_f32 v251, v228, v229
	v_cvt_pk_bf16_f32 v252, v230, v231
	v_cvt_pk_bf16_f32 v253, v232, v233
	v_bitop3_b32 v93, v118, s47, v119 bitop3:0xde
	v_mul_f32_e32 v224, 0xbfb8aa3b, v153
	v_mul_f32_e32 v225, v153, v153
	v_mul_f32_e32 v234, v108, v224
	v_mul_f32_e32 v235, v109, v224
	v_mul_f32_e32 v236, v110, v224
	v_mul_f32_e32 v237, v111, v224
	v_mul_f32_e32 v238, v100, v224
; __host__ __device__ __forceinline__ size_t tiled_off(int row, int col, int K) { return ((size_t)(row >> 7) * (K >> 6) + (col >> 6)) * 8192 + (lds_byte(row & 127, col & 63) >> 1); }
; __device__ __forceinline__ unsigned cvt_pk_bf16(float lo, float hi) { unsigned r; asm volatile("v_cvt_pk_bf16_f32 %0, %1, %2" : "=v"(r) : "v"(lo), "v"(hi)); return r; }
; __device__ __forceinline__ float fast_sigmoid(float x) { return __builtin_amdgcn_rcpf(1.0f + __builtin_amdgcn_exp2f(x * -1.4426950408889634f)); }
;     __device__ __forceinline__ void operator()(const f32x4 (&acc)[2][2][4][2], const Unit& u, int wr, int wc, int fr, int fq, const PG8_LAS float* rtab) const {
;     ...
;             for (int m = 0; m < 4; ++m) { const float r = rs[ai][m]; float o[8];
; #pragma unroll
;                 for (int n = 0; n < 2; ++n) { const f32x4 a = acc[ai][0][m][n] * r + bv[n], g = acc[ai][1][m][n] * r + bg[n];
; #pragma unroll
;                     for (int e = 0; e < 4; ++e) o[4 * n + e] = (MODE == 0) ? a[e] * fast_sigmoid(g[e]) : a[e] * fast_sigmoid(a[e]) * g[e]; }
;                 u32x4 w; w.x = cvt_pk_bf16(o[0], o[1]); w.y = cvt_pk_bf16(o[2], o[3]); w.z = cvt_pk_bf16(o[4], o[5]); w.w = cvt_pk_bf16(o[6], o[7]);
;                 if (MODE == 1) *(u32x4*)(O + tiled_off(row0 + ai * HALF + m * 16, lcol, ldc)) = w;
;                 else *(u32x4*)(O + (size_t)(row0 + ai * HALF + m * 16) * ldc + lcol) = w; }
	v_mul_f32_e32 v239, v101, v224
	v_mul_f32_e32 v240, v102, v224
	v_mul_f32_e32 v241, v103, v224
	v_mul_f32_e32 v226, v108, v104
	v_mul_f32_e32 v227, v109, v105
	v_mul_f32_e32 v228, v110, v106
	v_mul_f32_e32 v229, v111, v107
	v_mul_f32_e32 v230, v100, v96
	v_mul_f32_e32 v231, v101, v97
	v_mul_f32_e32 v232, v102, v98
	v_mul_f32_e32 v233, v103, v99
	v_exp_f32_e32 v234, v234
	v_exp_f32_e32 v235, v235
	v_exp_f32_e32 v236, v236
	v_exp_f32_e32 v237, v237
	v_exp_f32_e32 v238, v238
	v_exp_f32_e32 v239, v239
	v_exp_f32_e32 v240, v240
	v_exp_f32_e32 v241, v241
	v_mul_f32_e32 v226, v226, v225
	v_mul_f32_e32 v227, v227, v225
	v_mul_f32_e32 v228, v228, v225
	v_mul_f32_e32 v229, v229, v225
	v_mul_f32_e32 v230, v230, v225
	v_mul_f32_e32 v231, v231, v225
	v_mul_f32_e32 v232, v232, v225
	v_mul_f32_e32 v233, v233, v225
	v_add_f32_e32 v234, 1.0, v234
	v_add_f32_e32 v235, 1.0, v235
	v_add_f32_e32 v236, 1.0, v236
	v_add_f32_e32 v237, 1.0, v237
	v_add_f32_e32 v238, 1.0, v238
	v_add_f32_e32 v239, 1.0, v239
	v_add_f32_e32 v240, 1.0, v240
	v_add_f32_e32 v241, 1.0, v241
	v_rcp_f32_e32 v234, v234
	v_rcp_f32_e32 v235, v235
	v_rcp_f32_e32 v236, v236
	v_rcp_f32_e32 v237, v237
	v_rcp_f32_e32 v238, v238
	v_rcp_f32_e32 v239, v239
	v_rcp_f32_e32 v240, v240
	v_rcp_f32_e32 v241, v241
	v_mul_f32_e32 v226, v226, v234
	v_mul_f32_e32 v227, v227, v235
	v_mul_f32_e32 v228, v228, v236
	v_mul_f32_e32 v229, v229, v237
	v_mul_f32_e32 v230, v230, v238
	v_mul_f32_e32 v231, v231, v239
	v_mul_f32_e32 v232, v232, v240
	v_mul_f32_e32 v233, v233, v241
	v_cvt_pk_bf16_f32 v246, v226, v227
	v_cvt_pk_bf16_f32 v247, v228, v229
	v_cvt_pk_bf16_f32 v248, v230, v231
	v_cvt_pk_bf16_f32 v249, v232, v233
	global_store_dwordx4 v93, v[246:249], s[54:55]
	s_or_b32 s47, s45, 32
	s_lshr_b32 s47, s47, 3
	s_and_b32 s47, s47, 12
	s_or_b32 s47, s47, s65
	s_lshl_b32 s47, s47, 10
	v_bitop3_b32 v87, v118, s47, v119 bitop3:0xde
	global_store_dwordx4 v87, v[250:253], s[54:55]
	s_or_b32 s45, s45, 48
	s_lshr_b32 s45, s45, 3
	s_and_b32 s45, s45, 14
	s_or_b32 s45, s45, s65
	s_lshl_b32 s45, s45, 10
	v_mul_f32_e32 v224, 0xbfb8aa3b, v141
	v_mul_f32_e32 v225, v141, v141
	v_mul_f32_e32 v234, v76, v224
	v_mul_f32_e32 v235, v77, v224
	v_mul_f32_e32 v236, v78, v224
	v_mul_f32_e32 v237, v79, v224
	v_mul_f32_e32 v238, v68, v224
	v_mul_f32_e32 v239, v69, v224
	v_mul_f32_e32 v240, v70, v224
	v_mul_f32_e32 v241, v71, v224
	v_mul_f32_e32 v226, v76, v72
	v_mul_f32_e32 v227, v77, v73
	v_mul_f32_e32 v228, v78, v74
	v_mul_f32_e32 v229, v79, v75
	v_mul_f32_e32 v230, v68, v64
	v_mul_f32_e32 v231, v69, v65
	v_mul_f32_e32 v232, v70, v66
	v_mul_f32_e32 v233, v71, v67
	v_exp_f32_e32 v234, v234
	v_exp_f32_e32 v235, v235
	v_exp_f32_e32 v236, v236
	v_exp_f32_e32 v237, v237
	v_exp_f32_e32 v238, v238
	v_exp_f32_e32 v239, v239
	v_exp_f32_e32 v240, v240
	v_exp_f32_e32 v241, v241
	v_mul_f32_e32 v226, v226, v225
	v_mul_f32_e32 v227, v227, v225
	v_mul_f32_e32 v228, v228, v225
	v_mul_f32_e32 v229, v229, v225
	v_mul_f32_e32 v230, v230, v225
	v_mul_f32_e32 v231, v231, v225
	v_mul_f32_e32 v232, v232, v225
	v_mul_f32_e32 v233, v233, v225
	v_add_f32_e32 v234, 1.0, v234
	v_add_f32_e32 v235, 1.0, v235
	v_add_f32_e32 v236, 1.0, v236
	v_add_f32_e32 v237, 1.0, v237
	v_add_f32_e32 v238, 1.0, v238
	v_add_f32_e32 v239, 1.0, v239
	v_add_f32_e32 v240, 1.0, v240
	v_add_f32_e32 v241, 1.0, v241
	v_rcp_f32_e32 v234, v234
	v_rcp_f32_e32 v235, v235
	v_rcp_f32_e32 v236, v236
	v_rcp_f32_e32 v237, v237
	v_rcp_f32_e32 v238, v238
	v_rcp_f32_e32 v239, v239
	v_rcp_f32_e32 v240, v240
	v_rcp_f32_e32 v241, v241
	v_mul_f32_e32 v226, v226, v234
	v_mul_f32_e32 v227, v227, v235
	v_mul_f32_e32 v228, v228, v236
	v_mul_f32_e32 v229, v229, v237
	v_mul_f32_e32 v230, v230, v238
	v_mul_f32_e32 v231, v231, v239
	v_mul_f32_e32 v232, v232, v240
	v_mul_f32_e32 v233, v233, v241
	v_cvt_pk_bf16_f32 v242, v226, v227
	v_cvt_pk_bf16_f32 v243, v228, v229
	v_cvt_pk_bf16_f32 v244, v230, v231
	v_cvt_pk_bf16_f32 v245, v232, v233
	v_bitop3_b32 v68, v118, s45, v119 bitop3:0xde
	global_store_dwordx4 v68, v[242:245], s[54:55]
	s_andn2_b64 vcc, exec, s[4:5]
	s_mov_b64 s[4:5], -1
	v_add_u32_e32 v67, 0x80, v151
	v_ashrrev_i32_e32 v66, 7, v67
	v_mul_f32_e32 v224, 0xbfb8aa3b, v138
	v_mul_f32_e32 v225, v138, v138
	v_mul_f32_e32 v234, v60, v224
	v_mul_f32_e32 v235, v61, v224
	v_mul_f32_e32 v236, v62, v224
	v_mul_f32_e32 v237, v63, v224
	v_mul_f32_e32 v238, v52, v224
	v_mul_f32_e32 v239, v53, v224
	v_mul_f32_e32 v240, v54, v224
	v_mul_f32_e32 v241, v55, v224
	v_mul_f32_e32 v226, v60, v56
	v_mul_f32_e32 v227, v61, v57
	v_mul_f32_e32 v228, v62, v58
	v_mul_f32_e32 v229, v63, v59
	v_mul_f32_e32 v230, v52, v48
	v_mul_f32_e32 v231, v53, v49
	v_mul_f32_e32 v232, v54, v50
	v_mul_f32_e32 v233, v55, v51
	v_exp_f32_e32 v234, v234
	v_exp_f32_e32 v235, v235
	v_exp_f32_e32 v236, v236
	v_exp_f32_e32 v237, v237
	v_exp_f32_e32 v238, v238
	v_exp_f32_e32 v239, v239
	v_exp_f32_e32 v240, v240
	v_exp_f32_e32 v241, v241
	v_mul_f32_e32 v226, v226, v225
	v_mul_f32_e32 v227, v227, v225
	v_mul_f32_e32 v228, v228, v225
	v_mul_f32_e32 v229, v229, v225
	v_mul_f32_e32 v230, v230, v225
	v_mul_f32_e32 v231, v231, v225
	v_mul_f32_e32 v232, v232, v225
	v_mul_f32_e32 v233, v233, v225
	v_add_f32_e32 v234, 1.0, v234
	v_add_f32_e32 v235, 1.0, v235
	v_add_f32_e32 v236, 1.0, v236
	v_add_f32_e32 v237, 1.0, v237
	v_add_f32_e32 v238, 1.0, v238
	v_add_f32_e32 v239, 1.0, v239
	v_add_f32_e32 v240, 1.0, v240
	v_add_f32_e32 v241, 1.0, v241
	v_rcp_f32_e32 v234, v234
	v_rcp_f32_e32 v235, v235
	v_rcp_f32_e32 v236, v236
	v_rcp_f32_e32 v237, v237
	v_rcp_f32_e32 v238, v238
	v_rcp_f32_e32 v239, v239
	v_rcp_f32_e32 v240, v240
	v_rcp_f32_e32 v241, v241
	v_mul_f32_e32 v226, v226, v234
; __host__ __device__ __forceinline__ size_t tiled_off(int row, int col, int K) { return ((size_t)(row >> 7) * (K >> 6) + (col >> 6)) * 8192 + (lds_byte(row & 127, col & 63) >> 1); }
; __device__ __forceinline__ unsigned cvt_pk_bf16(float lo, float hi) { unsigned r; asm volatile("v_cvt_pk_bf16_f32 %0, %1, %2" : "=v"(r) : "v"(lo), "v"(hi)); return r; }
; __device__ __forceinline__ float fast_sigmoid(float x) { return __builtin_amdgcn_rcpf(1.0f + __builtin_amdgcn_exp2f(x * -1.4426950408889634f)); }
;     __device__ __forceinline__ void operator()(const f32x4 (&acc)[2][2][4][2], const Unit& u, int wr, int wc, int fr, int fq, const PG8_LAS float* rtab) const {
;     ...
;             for (int m = 0; m < 4; ++m) { const float r = rs[ai][m]; float o[8];
; #pragma unroll
;                 for (int n = 0; n < 2; ++n) { const f32x4 a = acc[ai][0][m][n] * r + bv[n], g = acc[ai][1][m][n] * r + bg[n];
; #pragma unroll
;                     for (int e = 0; e < 4; ++e) o[4 * n + e] = (MODE == 0) ? a[e] * fast_sigmoid(g[e]) : a[e] * fast_sigmoid(a[e]) * g[e]; }
;                 u32x4 w; w.x = cvt_pk_bf16(o[0], o[1]); w.y = cvt_pk_bf16(o[2], o[3]); w.z = cvt_pk_bf16(o[4], o[5]); w.w = cvt_pk_bf16(o[6], o[7]);
;                 if (MODE == 1) *(u32x4*)(O + tiled_off(row0 + ai * HALF + m * 16, lcol, ldc)) = w;
;                 else *(u32x4*)(O + (size_t)(row0 + ai * HALF + m * 16) * ldc + lcol) = w; }
	v_mul_f32_e32 v227, v227, v235
	v_mul_f32_e32 v228, v228, v236
	v_mul_f32_e32 v229, v229, v237
	v_mul_f32_e32 v230, v230, v238
	v_mul_f32_e32 v231, v231, v239
	v_mul_f32_e32 v232, v232, v240
	v_mul_f32_e32 v233, v233, v241
	v_cvt_pk_bf16_f32 v246, v226, v227
	v_cvt_pk_bf16_f32 v247, v228, v229
	v_cvt_pk_bf16_f32 v248, v230, v231
	v_cvt_pk_bf16_f32 v249, v232, v233
	v_lshlrev_b32_e32 v55, 2, v67
	v_and_b32_e32 v55, 32, v55
	v_lshlrev_b32_e32 v54, 6, v67
	v_and_or_b32 v54, v54, s64, v143
	v_bitop3_b32 v130, v54, s66, v55 bitop3:0xde
	v_mul_lo_u32 v48, v66, 44
	v_ashrrev_i32_e32 v49, 31, v48
	v_lshl_add_u64 v[48:49], v[48:49], 0, s[52:53]
	v_lshlrev_b64 v[48:49], 14, v[48:49]
	v_lshl_add_u64 v[48:49], s[24:25], 0, v[48:49]
	v_lshl_add_u64 v[56:57], v[48:49], 0, v[130:131]
	global_store_dwordx4 v[56:57], v[246:249], off
	s_nop 0
	v_mul_f32_e32 v224, 0xbfb8aa3b, v139
	v_mul_f32_e32 v225, v139, v139
	v_mul_f32_e32 v234, v44, v224
	v_mul_f32_e32 v235, v45, v224
	v_mul_f32_e32 v236, v46, v224
	v_mul_f32_e32 v237, v47, v224
	v_mul_f32_e32 v238, v36, v224
	v_mul_f32_e32 v239, v37, v224
	v_mul_f32_e32 v240, v38, v224
	v_mul_f32_e32 v241, v39, v224
	v_mul_f32_e32 v226, v44, v40
	v_mul_f32_e32 v227, v45, v41
	v_mul_f32_e32 v228, v46, v42
	v_mul_f32_e32 v229, v47, v43
	v_mul_f32_e32 v230, v36, v32
	v_mul_f32_e32 v231, v37, v33
	v_mul_f32_e32 v232, v38, v34
	v_mul_f32_e32 v233, v39, v35
	v_exp_f32_e32 v234, v234
	v_exp_f32_e32 v235, v235
	v_exp_f32_e32 v236, v236
	v_exp_f32_e32 v237, v237
	v_exp_f32_e32 v238, v238
	v_exp_f32_e32 v239, v239
	v_exp_f32_e32 v240, v240
	v_exp_f32_e32 v241, v241
	v_mul_f32_e32 v226, v226, v225
	v_mul_f32_e32 v227, v227, v225
	v_mul_f32_e32 v228, v228, v225
	v_mul_f32_e32 v229, v229, v225
	v_mul_f32_e32 v230, v230, v225
	v_mul_f32_e32 v231, v231, v225
	v_mul_f32_e32 v232, v232, v225
	v_mul_f32_e32 v233, v233, v225
	v_add_f32_e32 v234, 1.0, v234
	v_add_f32_e32 v235, 1.0, v235
	v_add_f32_e32 v236, 1.0, v236
	v_add_f32_e32 v237, 1.0, v237
	v_add_f32_e32 v238, 1.0, v238
	v_add_f32_e32 v239, 1.0, v239
	v_add_f32_e32 v240, 1.0, v240
	v_add_f32_e32 v241, 1.0, v241
	v_rcp_f32_e32 v234, v234
	v_rcp_f32_e32 v235, v235
	v_rcp_f32_e32 v236, v236
	v_rcp_f32_e32 v237, v237
	v_rcp_f32_e32 v238, v238
	v_rcp_f32_e32 v239, v239
	v_rcp_f32_e32 v240, v240
	v_rcp_f32_e32 v241, v241
	v_mul_f32_e32 v226, v226, v234
	v_mul_f32_e32 v227, v227, v235
	v_mul_f32_e32 v228, v228, v236
	v_mul_f32_e32 v229, v229, v237
	v_mul_f32_e32 v230, v230, v238
	v_mul_f32_e32 v231, v231, v239
	v_mul_f32_e32 v232, v232, v240
	v_mul_f32_e32 v233, v233, v241
	v_cvt_pk_bf16_f32 v250, v226, v227
	v_cvt_pk_bf16_f32 v251, v228, v229
	v_cvt_pk_bf16_f32 v252, v230, v231
	v_cvt_pk_bf16_f32 v253, v232, v233
	v_add_u32_e32 v36, 0x90, v151
	v_lshrrev_b32_e32 v37, 3, v36
	v_and_or_b32 v37, v37, 10, s65
	v_lshlrev_b32_e32 v38, 6, v36
	v_lshlrev_b32_e32 v36, 2, v36
	v_and_or_b32 v38, v38, s64, v143
	v_lshlrev_b32_e32 v37, 10, v37
	v_and_b32_e32 v36, 32, v36
	v_bitop3_b32 v130, v38, v37, v36 bitop3:0xde
	v_mul_f32_e32 v224, 0xbfb8aa3b, v136
	v_mul_f32_e32 v225, v136, v136
	v_mul_f32_e32 v234, v28, v224
	v_mul_f32_e32 v235, v29, v224
	v_mul_f32_e32 v236, v30, v224
	v_mul_f32_e32 v237, v31, v224
	v_mul_f32_e32 v238, v20, v224
	v_mul_f32_e32 v239, v21, v224
	v_mul_f32_e32 v240, v22, v224
	v_mul_f32_e32 v241, v23, v224
	v_mul_f32_e32 v226, v28, v24
	v_mul_f32_e32 v227, v29, v25
	v_mul_f32_e32 v228, v30, v26
	v_mul_f32_e32 v229, v31, v27
	v_mul_f32_e32 v230, v20, v16
	v_mul_f32_e32 v231, v21, v17
	v_mul_f32_e32 v232, v22, v18
	v_mul_f32_e32 v233, v23, v19
	v_exp_f32_e32 v234, v234
	v_exp_f32_e32 v235, v235
	v_exp_f32_e32 v236, v236
	v_exp_f32_e32 v237, v237
	v_exp_f32_e32 v238, v238
	v_exp_f32_e32 v239, v239
	v_exp_f32_e32 v240, v240
	v_exp_f32_e32 v241, v241
	v_mul_f32_e32 v226, v226, v225
	v_mul_f32_e32 v227, v227, v225
	v_mul_f32_e32 v228, v228, v225
	v_mul_f32_e32 v229, v229, v225
	v_mul_f32_e32 v230, v230, v225
	v_mul_f32_e32 v231, v231, v225
	v_mul_f32_e32 v232, v232, v225
	v_mul_f32_e32 v233, v233, v225
	v_add_f32_e32 v234, 1.0, v234
	v_add_f32_e32 v235, 1.0, v235
	v_add_f32_e32 v236, 1.0, v236
	v_add_f32_e32 v237, 1.0, v237
; __host__ __device__ __forceinline__ size_t tiled_off(int row, int col, int K) { return ((size_t)(row >> 7) * (K >> 6) + (col >> 6)) * 8192 + (lds_byte(row & 127, col & 63) >> 1); }
; __device__ __forceinline__ unsigned cvt_pk_bf16(float lo, float hi) { unsigned r; asm volatile("v_cvt_pk_bf16_f32 %0, %1, %2" : "=v"(r) : "v"(lo), "v"(hi)); return r; }
; __device__ __forceinline__ float fast_sigmoid(float x) { return __builtin_amdgcn_rcpf(1.0f + __builtin_amdgcn_exp2f(x * -1.4426950408889634f)); }
;     __device__ __forceinline__ void operator()(const f32x4 (&acc)[2][2][4][2], const Unit& u, int wr, int wc, int fr, int fq, const PG8_LAS float* rtab) const {
;     ...
;             for (int m = 0; m < 4; ++m) { const float r = rs[ai][m]; float o[8];
; #pragma unroll
;                 for (int n = 0; n < 2; ++n) { const f32x4 a = acc[ai][0][m][n] * r + bv[n], g = acc[ai][1][m][n] * r + bg[n];
; #pragma unroll
;                     for (int e = 0; e < 4; ++e) o[4 * n + e] = (MODE == 0) ? a[e] * fast_sigmoid(g[e]) : a[e] * fast_sigmoid(a[e]) * g[e]; }
;                 u32x4 w; w.x = cvt_pk_bf16(o[0], o[1]); w.y = cvt_pk_bf16(o[2], o[3]); w.z = cvt_pk_bf16(o[4], o[5]); w.w = cvt_pk_bf16(o[6], o[7]);
;                 if (MODE == 1) *(u32x4*)(O + tiled_off(row0 + ai * HALF + m * 16, lcol, ldc)) = w;
;                 else *(u32x4*)(O + (size_t)(row0 + ai * HALF + m * 16) * ldc + lcol) = w; }
	v_add_f32_e32 v238, 1.0, v238
	v_add_f32_e32 v239, 1.0, v239
	v_add_f32_e32 v240, 1.0, v240
	v_add_f32_e32 v241, 1.0, v241
	v_rcp_f32_e32 v234, v234
	v_rcp_f32_e32 v235, v235
	v_rcp_f32_e32 v236, v236
	v_rcp_f32_e32 v237, v237
	v_rcp_f32_e32 v238, v238
	v_rcp_f32_e32 v239, v239
	v_rcp_f32_e32 v240, v240
	v_rcp_f32_e32 v241, v241
	v_mul_f32_e32 v226, v226, v234
	v_mul_f32_e32 v227, v227, v235
	v_mul_f32_e32 v228, v228, v236
	v_mul_f32_e32 v229, v229, v237
	v_mul_f32_e32 v230, v230, v238
	v_mul_f32_e32 v231, v231, v239
	v_mul_f32_e32 v232, v232, v240
	v_mul_f32_e32 v233, v233, v241
	v_cvt_pk_bf16_f32 v242, v226, v227
	v_cvt_pk_bf16_f32 v243, v228, v229
	v_cvt_pk_bf16_f32 v244, v230, v231
	v_cvt_pk_bf16_f32 v245, v232, v233
	v_lshl_add_u64 v[28:29], v[48:49], 0, v[130:131]
	global_store_dwordx4 v[28:29], v[250:253], off
	v_add_u32_e32 v20, 0xa0, v151
	v_lshrrev_b32_e32 v21, 3, v20
	v_and_or_b32 v21, v21, 12, s65
	v_lshlrev_b32_e32 v22, 6, v20
	v_lshlrev_b32_e32 v20, 2, v20
	v_and_or_b32 v22, v22, s64, v143
	v_lshlrev_b32_e32 v21, 10, v21
	v_and_b32_e32 v20, 32, v20
	v_bitop3_b32 v130, v22, v21, v20 bitop3:0xde
	v_lshl_add_u64 v[22:23], v[48:49], 0, v[130:131]
	global_store_dwordx4 v[22:23], v[242:245], off
	v_mul_f32_e32 v224, 0xbfb8aa3b, v137
	v_mul_f32_e32 v225, v137, v137
	v_mul_f32_e32 v234, v12, v224
	v_mul_f32_e32 v235, v13, v224
	v_mul_f32_e32 v236, v14, v224
	v_mul_f32_e32 v237, v15, v224
	v_mul_f32_e32 v238, v4, v224
	v_mul_f32_e32 v239, v5, v224
	v_mul_f32_e32 v240, v6, v224
	v_mul_f32_e32 v241, v7, v224
	v_mul_f32_e32 v226, v12, v8
	v_mul_f32_e32 v227, v13, v9
	v_mul_f32_e32 v228, v14, v10
	v_mul_f32_e32 v229, v15, v11
	v_mul_f32_e32 v230, v4, v0
	v_mul_f32_e32 v231, v5, v1
	v_mul_f32_e32 v232, v6, v2
	v_mul_f32_e32 v233, v7, v3
	v_exp_f32_e32 v234, v234
	v_exp_f32_e32 v235, v235
	v_exp_f32_e32 v236, v236
	v_exp_f32_e32 v237, v237
	v_exp_f32_e32 v238, v238
	v_exp_f32_e32 v239, v239
	v_exp_f32_e32 v240, v240
	v_exp_f32_e32 v241, v241
	v_mul_f32_e32 v226, v226, v225
	v_mul_f32_e32 v227, v227, v225
	v_mul_f32_e32 v228, v228, v225
	v_mul_f32_e32 v229, v229, v225
	v_mul_f32_e32 v230, v230, v225
	v_mul_f32_e32 v231, v231, v225
	v_mul_f32_e32 v232, v232, v225
	v_mul_f32_e32 v233, v233, v225
	v_add_f32_e32 v234, 1.0, v234
	v_add_f32_e32 v235, 1.0, v235
	v_add_f32_e32 v236, 1.0, v236
	v_add_f32_e32 v237, 1.0, v237
	v_add_f32_e32 v238, 1.0, v238
	v_add_f32_e32 v239, 1.0, v239
	v_add_f32_e32 v240, 1.0, v240
	v_add_f32_e32 v241, 1.0, v241
	v_rcp_f32_e32 v234, v234
	v_rcp_f32_e32 v235, v235
	v_rcp_f32_e32 v236, v236
	v_rcp_f32_e32 v237, v237
	v_rcp_f32_e32 v238, v238
	v_rcp_f32_e32 v239, v239
	v_rcp_f32_e32 v240, v240
	v_rcp_f32_e32 v241, v241
	v_mul_f32_e32 v226, v226, v234
	v_mul_f32_e32 v227, v227, v235
	v_mul_f32_e32 v228, v228, v236
	v_mul_f32_e32 v229, v229, v237
	v_mul_f32_e32 v230, v230, v238
	v_mul_f32_e32 v231, v231, v239
	v_mul_f32_e32 v232, v232, v240
	v_mul_f32_e32 v233, v233, v241
	v_cvt_pk_bf16_f32 v246, v226, v227
	v_cvt_pk_bf16_f32 v247, v228, v229
	v_cvt_pk_bf16_f32 v248, v230, v231
	v_cvt_pk_bf16_f32 v249, v232, v233
	v_add_u32_e32 v4, 0xb0, v151
	v_lshrrev_b32_e32 v5, 3, v4
	v_and_or_b32 v5, v5, 14, s65
	v_lshlrev_b32_e32 v6, 6, v4
	v_lshlrev_b32_e32 v4, 2, v4
	v_and_or_b32 v6, v6, s64, v143
	v_lshlrev_b32_e32 v5, 10, v5
	v_and_b32_e32 v4, 32, v4
	v_bitop3_b32 v130, v6, v5, v4 bitop3:0xde
	v_lshl_add_u64 v[4:5], v[48:49], 0, v[130:131]
	global_store_dwordx4 v[4:5], v[246:249], off
	s_cbranch_vccnz .LBB0_1621
	s_and_saveexec_b64 s[4:5], s[2:3]
	s_cbranch_execz .LBB0_1631
	s_lshl_b32 s45, s72, 10
	s_and_b32 s45, s45, 0x400
	s_waitcnt vmcnt(8)
	v_pk_add_f32 v[2:3], v[162:163], v[166:167]
	v_pk_add_f32 v[0:1], v[160:161], v[164:165]
	v_pk_add_f32 v[4:5], v[170:171], v[174:175]
	v_pk_add_f32 v[6:7], v[168:169], v[172:173]
	v_pk_add_f32 v[2:3], v[2:3], v[4:5]
	v_pk_add_f32 v[0:1], v[0:1], v[6:7]
	s_nop 0
	v_pk_mov_b32 v[4:5], v[0:1], v[2:3] op_sel:[1,0]
	v_mov_b32_e32 v1, v3
	v_pk_add_f32 v[0:1], v[4:5], v[0:1]
	s_nop 0
	v_add_f32_e32 v0, v0, v1
	v_fmamk_f32 v0, v0, 0x3a800000, v150
	v_rsq_f32_e32 v0, v0
	v_add_u32_e32 v1, s45, v145
	ds_write_b32 v1, v0
